# merge phase: all four gates per GEMM (B tile rows gathered from the four gate panels for a 64-column block), epilogue sums the four gated branch products in registers and stages to mg; the bf16 runnin
# speedup vs baseline: 1.0403x; 1.0092x over previous
; DI int half_() { return __builtin_amdgcn_readfirstlane((int)(threadIdx.x >> 8)); }
; __global__ void __launch_bounds__(512, 2) mega(Params p_unused, int ph0, int ph1) {
;   __shared__ __attribute__((aligned(16))) unsigned char lds_all[LDS_BYTES];
;   unsigned char* ldsb = lds_all + half_() * LDS_HALF;
;   cg::grid_group grid = cg::this_grid();
;   for (int ph = ph0; ph < ph1; ++ph) {
;     const __attribute__((address_space(4))) Params* pp = (const __attribute__((address_space(4))) Params*)__builtin_amdgcn_kernarg_segment_ptr();
;     asm volatile("" : "+s"(pp));
;     PREF p = *pp;
;     if (ph1 < 0) grid.sync();
;     if (ph > ph0) grid_barrier(p.bar, (unsigned)(ph - ph0));
;     if (ph == 0) { run_phase<9>(p, 0, ldsb, lds_all); continue; }
;     int l = (ph - 1) / NPH_LAYER; const int j = (ph - 1) % NPH_LAYER;
;     asm volatile("" : "+s"(l));
.LBB0_1:
	s_lshr_b32 s33, s0, 8
	v_readlane_b32 s0, v254, 1
	v_readlane_b32 s1, v254, 2
	s_add_u32 s2, s0, 0x1a8
	s_addc_u32 s3, s1, 0
	v_writelane_b32 v254, s2, 5
	v_lshrrev_b32_e32 v1, 20, v0
	v_lshrrev_b32_e32 v0, 10, v0
	v_writelane_b32 v254, s3, 6
	v_or_b32_e32 v0, v0, v1
	s_movk_i32 s2, 0x3ff
	v_and_or_b32 v0, v0, s2, v168
	v_readlane_b32 s8, v254, 3
	v_cmp_eq_u32_e64 s[2:3], 0, v0
	v_readlane_b32 s9, v254, 4
	s_load_dword s5, s[0:1], 0x1a8
	v_writelane_b32 v254, s2, 7
	s_cmp_lt_i32 s9, 0
	s_cselect_b64 s[0:1], -1, 0
	v_writelane_b32 v254, s3, 8
	v_cmp_eq_u32_e64 s[2:3], 0, v168
	s_waitcnt lgkmcnt(0)
	s_lshr_b32 s45, s5, 3
	s_mul_i32 s33, s33, 0x12400
	v_writelane_b32 v254, s2, 9
	v_cndmask_b32_e64 v0, 0, 1, s[0:1]
	v_cmp_ne_u32_e64 s[0:1], 1, v0
	v_writelane_b32 v254, s3, 10
	v_mbcnt_lo_u32_b32 v0, -1, 0
	v_readlane_b32 s4, v254, 0
	s_and_b32 s2, s4, 15
	s_xor_b32 s3, s2, 15
	s_add_i32 s3, s5, s3
	s_lshr_b32 s3, s3, 4
	s_lshl_b32 s2, s2, 6
	s_lshr_b32 s46, s4, 3
	s_cmpk_lt_u32 s4, 0x200
	v_writelane_b32 v254, s3, 11
	s_cselect_b64 s[6:7], -1, 0
	s_lshl_b32 s3, s4, 4
	s_and_b32 s47, s3, 0x70
	s_lshl_b32 s3, s4, 3
	s_lshl_b32 s48, s5, 3
	v_writelane_b32 v254, s6, 12
	s_cmpk_lt_i32 s4, 0x100
	s_mov_b32 s53, 0
	v_writelane_b32 v254, s7, 13
	s_cselect_b64 s[6:7], -1, 0
	v_writelane_b32 v254, s6, 14
	s_ashr_i32 s49, s48, 31
	s_lshl_b32 s64, s5, 9
	v_writelane_b32 v254, s7, 15
	s_add_i32 s6, s33, 0x12000
	v_writelane_b32 v254, s6, 16
	s_lshl_b32 s6, s4, 9
	v_writelane_b32 v254, s6, 17
	s_lshl_b64 s[6:7], s[48:49], 11
	v_writelane_b32 v254, s6, 18
	s_ashr_i32 s65, s64, 31
	s_lshl_b32 s70, s4, 1
	v_writelane_b32 v254, s7, 19
	v_writelane_b32 v254, s3, 20
	s_addk_i32 s3, 0x4000
	v_writelane_b32 v254, s3, 21
	s_lshl_b32 s3, s4, 8
	v_writelane_b32 v254, s3, 22
	s_lshl_b32 s3, s5, 8
	v_writelane_b32 v254, s3, 23
	s_add_i32 s3, s33, 0x4000
	v_writelane_b32 v254, s3, 24
	s_lshl_b32 s3, s4, 6
	v_writelane_b32 v254, s3, 25
	s_lshl_b64 s[6:7], s[64:65], 4
	v_writelane_b32 v254, s6, 26
	s_lshl_b32 s3, s5, 10
	s_lshl_b32 s71, s5, 1
	v_writelane_b32 v254, s7, 27
	s_lshl_b64 s[6:7], s[64:65], 5
	v_writelane_b32 v254, s6, 28
	s_lshl_b32 s81, s4, 7
	s_lshl_b32 s84, s5, 7
	v_writelane_b32 v254, s7, 29
	s_lshl_b64 s[6:7], s[48:49], 12
	v_writelane_b32 v254, s6, 30
	s_lshl_b32 s85, s5, 6
	s_movk_i32 s66, 0x200
	v_writelane_b32 v254, s7, 31
	v_writelane_b32 v254, s5, 32
	v_writelane_b32 v254, s3, 33
	s_lshl_b64 s[4:5], s[64:65], 2
	v_writelane_b32 v254, s4, 34
	v_and_b32_e32 v169, 0xff, v168
	s_movk_i32 s67, 0x100
	v_writelane_b32 v254, s5, 35
	v_writelane_b32 v254, s0, 36
	s_lshl_b64 s[72:73], s[64:65], 6
	v_mov_b32_e32 v1, 0
	v_writelane_b32 v254, s1, 37
	s_lshl_b32 s0, s2, 2
	v_writelane_b32 v254, s0, 38
	v_writelane_b32 v254, s45, 39
	v_writelane_b32 v254, s46, 40
	v_writelane_b32 v254, s47, 41
	s_mov_b32 s0, s48
	v_writelane_b32 v254, s0, 42
	s_mov_b32 s88, 0x10000
	v_mov_b32_e32 v170, 0x1000
	v_writelane_b32 v254, s1, 43
	s_mov_b32 s0, s64
	s_mov_b64 s[76:77], 0x80
	s_mov_b64 s[78:79], 0x40080
	s_mov_b64 s[42:43], 0x12b0100
	s_mov_b64 s[82:83], 0x100
	s_mov_b64 s[86:87], 0x40100
	s_mov_b64 s[90:91], 0x180
	s_movk_i32 s89, 0x180
	s_movk_i32 s92, 0x210
	s_movk_i32 s93, 0x80
	v_mov_b32_e32 v171, 0x3727c5ac
	s_mov_b32 s61, 0x800000
	s_movk_i32 s80, 0x1000
	s_mov_b64 s[50:51], 0x580100
	s_mov_b64 s[38:39], 0x980100
	s_mov_b64 s[4:5], 0x580180
	s_mov_b64 s[74:75], 0x980180
	s_movk_i32 s60, 0x1540
	s_movk_i32 s96, 0x300
	s_movk_i32 s97, 0x90
	s_mov_b32 s94, 0xff800000
	v_mbcnt_hi_u32_b32 v172, -1, v0
	v_mov_b32_e32 v163, 1.0
	s_mov_b64 s[2:3], 0xaa000
	v_mov_b32_e32 v173, 0x358637bd
	s_movk_i32 s95, 0x400
	s_mov_b64 s[6:7], 0x40180
	s_movk_i32 s58, 0xaa0
	s_movk_i32 s59, 0x600
	s_movk_i32 s54, 0x2a80
	v_mov_b32_e32 v174, 0x3c0881c4
	v_mov_b32_e32 v175, 0xbab64f3b
	v_mov_b32_e32 v176, 0xff800000
	v_mov_b32_e32 v177, 0x7f800000
	v_not_b32_e32 v178, 63
	v_not_b32_e32 v179, 31
	v_mov_b32_e32 v180, 0x7fc00000
	v_mov_b32_e32 v181, 0x37000000
	s_mov_b32 s34, s8
	v_writelane_b32 v254, s0, 44
	s_nop 1
	v_writelane_b32 v254, s1, 45
	s_branch .LBB0_4

; DI void lds_barrier() { asm volatile("s_waitcnt lgkmcnt(0)\n\ts_barrier" ::: "memory"); }
; DI int tid512() { int t = threadIdx.x; asm volatile("" : "+v"(t)); return t; }
; #define G_WAIT_V(n) asm volatile("s_waitcnt vmcnt(" #n ")" ::: "memory")
; #define G_BAR __builtin_amdgcn_s_barrier()
;     ...
;   const int t = tid512();
;   const int wid = t >> 6, lane = t & 63, wr = wid >> 2, wc = wid & 3, fr = lane & 15, fq = lane >> 4;
;   int r0, c0, r1, c1;
;   g_stage_rc(t * 16, r0, c0); g_stage_rc(t * 16 + 8192, r1, c1);
;   const int oa0 = r0 * LDA + c0, oa1 = r1 * LDA + c1, ob0 = r0 * LDB + c0, ob1 = r1 * LDB + c1;
;   const int obr = fr * 64 + fq * 16, rdo = obr ^ (((obr >> 9) & 1) << 5);
;   bf16x8 At[4][2], B0[2][2], B1[2][2];
;   constexpr int nt = K / 64;
;   lds_barrier();
;   G_STAGE(G_SB(0, 0), B, ob0, ob1, LDB, 0, KB(0)); G_STAGE(G_SA(0, 0), A, oa0, oa1, LDA, 0, KA(0));
;   G_STAGE(G_SB(0, 1), B, ob0, ob1, LDB, 128, KB(0)); G_STAGE(G_SA(0, 1), A, oa0, oa1, LDA, 128, KA(0));
;   if (wr == 1) G_BAR;
;   G_WAIT_V(4); G_BAR;
;   G_STAGE(G_SB(1, 0), B, ob0, ob1, LDB, 0, KB(1)); G_STAGE(G_SA(1, 0), A, oa0, oa1, LDA, 0, KA(1)); G_STAGE(G_SB(1, 1), B, ob0, ob1, LDB, 128, KB(1));
;   G_WAIT_V(6); G_BAR;
; DI void merge_phase(PREF p, int l, unsigned char* lds_all) {
;     ...
; #pragma unroll 1
;     for (int n = 0; n < 4; ++n) {
;       f32x4 acc[2][2][4][2]; zero_acc256(acc);
;       gemm256<1024, 1024, 1024>(acc, p.X + (size_t)mt * 256 * 1024, W + O_WM + ((size_t)n * 1024 + dt * 256) * 1024, shm, p);
.LBB0_101:
	s_add_i32 s23, s23, 1
	s_add_u32 s40, s40, 0x20000
	s_addc_u32 s41, s41, 0
	s_cmp_lg_u32 s23, 4
	s_cbranch_scc0 .LBB0_87
.LBB0_102:
	s_lshl_b32 s52, s23, 6
	s_add_u32 s0, s52, s28
	v_mov_b32_e32 v0, v168
	s_addc_u32 s1, 0, s29
	s_lshl_b64 s[0:1], s[0:1], 11
	v_lshlrev_b32_e32 v143, 4, v0
	v_and_b32_e32 v2, 32, v0
	v_lshrrev_b32_e32 v4, 1, v0
	v_bitop3_b32 v2, v143, v2, 48 bitop3:0x6c
	s_add_u32 s8, s65, s0
	v_ashrrev_i32_e32 v10, 3, v0
	v_bfe_u32 v13, v0, 2, 4
	s_mov_b32 s0, 0x3ffff0
	v_and_b32_e32 v11, 32, v4
	v_lshrrev_b32_e32 v12, 1, v2
	v_add_u32_e32 v144, 0x2000, v143
	v_and_or_b32 v3, v10, s0, v13
	v_or_b32_e32 v2, v12, v11
	v_ashrrev_i32_e32 v15, 7, v144
	v_and_or_b32 v4, v15, s0, v13
	v_lshl_or_b32 v132, v3, 10, v2
	v_lshl_or_b32 v130, v4, 10, v2
	v_bfe_u32 v182, v3, 4, 1
	v_lshlrev_b32_e32 v182, 20, v182
	v_lshrrev_b32_e32 v184, 5, v3
	v_lshlrev_b32_e32 v184, 4, v184
	v_and_b32_e32 v183, 15, v3
	v_add_u32_e32 v184, v184, v183
	v_lshl_or_b32 v182, v184, 10, v182
	v_or_b32_e32 v182, v182, v2
	v_lshlrev_b32_e32 v182, 1, v182
	v_mov_b32_e32 v183, 0
	v_add_u32_e32 v184, 0x10000, v182
	v_mov_b32_e32 v185, 0
	v_ashrrev_i32_e32 v133, 31, v132
	v_add_u32_e32 v146, 0x10000, v143
	s_addc_u32 s9, s68, s1
	v_lshlrev_b64 v[16:17], 1, v[132:133]
	v_readfirstlane_b32 s0, v146
	v_ashrrev_i32_e32 v131, 31, v130
	v_add_u32_e32 v147, 0x12000, v143
	s_waitcnt lgkmcnt(0)
	s_barrier
	v_lshl_add_u64 v[2:3], s[8:9], 0, v[182:183]
	s_mov_b32 m0, s0
	v_lshlrev_b64 v[18:19], 1, v[130:131]
	v_readfirstlane_b32 s0, v147
	global_load_lds_dwordx4 v[2:3], off
	v_lshl_add_u64 v[6:7], s[8:9], 0, v[184:185]
	s_mov_b32 m0, s0
	v_readfirstlane_b32 s0, v143
	global_load_lds_dwordx4 v[6:7], off
	v_lshl_add_u64 v[8:9], s[26:27], 0, v[16:17]
	s_mov_b32 m0, s0
	v_readfirstlane_b32 s0, v144
	global_load_lds_dwordx4 v[8:9], off
	s_mov_b32 m0, s0
	s_add_u32 s0, s8, 0x400000
	v_add_u32_e32 v149, 0x14000, v143
	v_lshl_add_u64 v[4:5], s[26:27], 0, v[18:19]
	s_addc_u32 s1, s9, 0
	v_readfirstlane_b32 s10, v149
	global_load_lds_dwordx4 v[4:5], off
	v_lshl_add_u64 v[20:21], s[0:1], 0, v[182:183]
	s_mov_b32 m0, s10
	v_add_u32_e32 v150, 0x16000, v143
	global_load_lds_dwordx4 v[20:21], off
	v_lshl_add_u64 v[20:21], s[0:1], 0, v[184:185]
	v_readfirstlane_b32 s0, v150
	v_add_u32_e32 v151, 0x4000, v143
	s_mov_b32 m0, s0
	v_readfirstlane_b32 s0, v151
	v_add_u32_e32 v152, 0x6000, v143
	global_load_lds_dwordx4 v[20:21], off
	v_lshl_add_u64 v[16:17], s[30:31], 0, v[16:17]
	s_mov_b32 m0, s0
	v_readfirstlane_b32 s0, v152
	global_load_lds_dwordx4 v[16:17], off
	v_lshl_add_u64 v[16:17], s[30:31], 0, v[18:19]
	s_mov_b32 m0, s0
	v_ashrrev_i32_e32 v14, 8, v0
	global_load_lds_dwordx4 v[16:17], off
	v_cmp_eq_u32_e32 vcc, 1, v14
	s_and_saveexec_b64 s[10:11], vcc
	s_cbranch_execz .LBB0_104
	s_barrier
; #define G_WAIT_V(n) asm volatile("s_waitcnt vmcnt(" #n ")" ::: "memory")
; #define G_BAR __builtin_amdgcn_s_barrier()
;     ...
;   G_STAGE(G_SB(0, 0), B, ob0, ob1, LDB, 0, KB(0)); G_STAGE(G_SA(0, 0), A, oa0, oa1, LDA, 0, KA(0));
;   G_STAGE(G_SB(0, 1), B, ob0, ob1, LDB, 128, KB(0)); G_STAGE(G_SA(0, 1), A, oa0, oa1, LDA, 128, KA(0));
;   if (wr == 1) G_BAR;
;   G_WAIT_V(4); G_BAR;
;   G_STAGE(G_SB(1, 0), B, ob0, ob1, LDB, 0, KB(1)); G_STAGE(G_SA(1, 0), A, oa0, oa1, LDA, 0, KA(1)); G_STAGE(G_SB(1, 1), B, ob0, ob1, LDB, 128, KB(1));
;   G_WAIT_V(6); G_BAR;
;   for (int tt = 0; tt < nt - 2; tt += 2) {
; DI void zero_acc256(f32x4 (&a)[2][2][4][2]) {
; #pragma unroll
;   for (int i = 0; i < 2; ++i)
; #pragma unroll
;     for (int j = 0; j < 2; ++j)
; #pragma unroll
;       for (int m = 0; m < 4; ++m)
; #pragma unroll
;         for (int n = 0; n < 2; ++n)
; #pragma unroll
;           for (int e = 0; e < 4; ++e) a[i][j][m][n][e] = 0.f;
; }
.LBB0_104:
	s_or_b64 exec, exec, s[10:11]
	v_add_u32_e32 v153, 0x18000, v143
	v_add_u32_e32 v154, 0x1a000, v143
	v_readfirstlane_b32 s0, v153
	v_lshl_add_u64 v[2:3], v[2:3], 0, s[76:77]
	s_mov_b32 m0, s0
	v_readfirstlane_b32 s0, v154
	v_add_u32_e32 v155, 0x8000, v143
	s_waitcnt vmcnt(4)
	s_barrier
	global_load_lds_dwordx4 v[2:3], off
	v_lshl_add_u64 v[2:3], v[6:7], 0, s[76:77]
	s_mov_b32 m0, s0
	v_readfirstlane_b32 s0, v155
	v_add_u32_e32 v156, 0xa000, v143
	global_load_lds_dwordx4 v[2:3], off
	v_lshl_add_u64 v[2:3], v[8:9], 0, s[76:77]
	s_mov_b32 m0, s0
	v_readfirstlane_b32 s0, v156
	global_load_lds_dwordx4 v[2:3], off
	s_mov_b32 m0, s0
	s_add_u32 s0, s8, 0x400080
	v_add_u32_e32 v157, 0x1c000, v143
	v_lshl_add_u64 v[2:3], v[4:5], 0, s[76:77]
	s_addc_u32 s1, s9, 0
	v_readfirstlane_b32 s8, v157
	global_load_lds_dwordx4 v[2:3], off
	v_lshl_add_u64 v[2:3], v[182:183], 0, s[0:1]
	s_mov_b32 m0, s8
	v_add_u32_e32 v159, 0x1e000, v143
	global_load_lds_dwordx4 v[2:3], off
	v_lshl_add_u64 v[2:3], v[184:185], 0, s[0:1]
	v_readfirstlane_b32 s0, v159
	s_mov_b32 m0, s0
	v_lshlrev_b32_e32 v17, 6, v0
	global_load_lds_dwordx4 v[2:3], off
	v_lshlrev_b32_e32 v2, 10, v15
	v_and_b32_e32 v2, 0xffffc000, v2
	v_lshlrev_b32_e32 v4, 10, v13
	v_lshlrev_b32_e32 v5, 10, v10
	v_and_b32_e32 v16, 48, v0
	v_and_b32_e32 v18, 0x3c0, v17
	v_lshlrev_b32_e32 v20, 2, v0
	v_or3_b32 v2, v12, v2, v4
	v_and_b32_e32 v5, 0xffffc000, v5
	v_or_b32_e32 v19, v18, v16
	v_and_b32_e32 v20, 32, v20
	s_mov_b32 s0, 0x14000
	v_add_u32_e32 v2, v2, v11
	v_or3_b32 v4, v12, v5, v4
	v_bitop3_b32 v8, v19, s0, v20 bitop3:0xde
	s_mov_b32 s0, 0x18000
	v_ashrrev_i32_e32 v3, 31, v2
	v_add_u32_e32 v4, v4, v11
	s_waitcnt vmcnt(6)
	v_bitop3_b32 v9, v19, s0, v20 bitop3:0xde
	s_mov_b32 s0, 0x1c000
	v_lshlrev_b64 v[2:3], 1, v[2:3]
	v_ashrrev_i32_e32 v5, 31, v4
	v_bitop3_b32 v16, v18, v20, v16 bitop3:0x36
	v_bitop3_b32 v6, v19, s88, v20 bitop3:0xde
	v_lshlrev_b32_e32 v7, 13, v14
	v_bitop3_b32 v14, v19, s0, v20 bitop3:0xde
	v_and_b32_e32 v17, 0x3000, v17
	v_lshl_add_u64 v[134:135], s[26:27], 0, v[2:3]
	v_lshlrev_b64 v[4:5], 1, v[4:5]
	v_lshl_add_u64 v[138:139], s[40:41], 0, v[184:185]
	v_mov_b32_e32 v2, 0
	v_lshl_add_u64 v[136:137], s[26:27], 0, v[4:5]
	v_lshl_add_u64 v[140:141], s[40:41], 0, v[182:183]
	s_mov_b32 s10, -2
	s_mov_b64 s[8:9], 0
	v_add_u32_e32 v160, v6, v17
	v_add_u32_e32 v142, v16, v7
	v_add_u32_e32 v158, v8, v17
	v_add_u32_e32 v148, v9, v17
	v_add_u32_e32 v145, v14, v17
	v_mov_b32_e32 v3, v2
	v_mov_b32_e32 v4, v2
	v_mov_b32_e32 v5, v2
	v_mov_b32_e32 v6, v2
	v_mov_b32_e32 v7, v2
	v_mov_b32_e32 v8, v2
	v_mov_b32_e32 v9, v2
	v_mov_b32_e32 v10, v2
	v_mov_b32_e32 v11, v2
	v_mov_b32_e32 v12, v2
	v_mov_b32_e32 v13, v2
	v_mov_b32_e32 v14, v2
	v_mov_b32_e32 v15, v2
	v_mov_b32_e32 v16, v2
	v_mov_b32_e32 v17, v2
	v_mov_b32_e32 v18, v2
	v_mov_b32_e32 v19, v2
	v_mov_b32_e32 v20, v2
	v_mov_b32_e32 v21, v2
	v_mov_b32_e32 v22, v2
	v_mov_b32_e32 v23, v2
	v_mov_b32_e32 v24, v2
	v_mov_b32_e32 v25, v2
	v_mov_b32_e32 v26, v2
	v_mov_b32_e32 v27, v2
	v_mov_b32_e32 v28, v2
	v_mov_b32_e32 v29, v2
	v_mov_b32_e32 v30, v2
	v_mov_b32_e32 v31, v2
	v_mov_b32_e32 v32, v2
	v_mov_b32_e32 v33, v2
	v_mov_b32_e32 v34, v2
	v_mov_b32_e32 v35, v2
	v_mov_b32_e32 v36, v2
	v_mov_b32_e32 v37, v2
	v_mov_b32_e32 v38, v2
	v_mov_b32_e32 v39, v2
	v_mov_b32_e32 v40, v2
	v_mov_b32_e32 v41, v2
	v_mov_b32_e32 v42, v2
	v_mov_b32_e32 v43, v2
	v_mov_b32_e32 v44, v2
	v_mov_b32_e32 v45, v2
	v_mov_b32_e32 v46, v2
	v_mov_b32_e32 v47, v2
	v_mov_b32_e32 v48, v2
	v_mov_b32_e32 v49, v2
	v_mov_b32_e32 v50, v2
	v_mov_b32_e32 v51, v2
	v_mov_b32_e32 v52, v2
	v_mov_b32_e32 v53, v2
	v_mov_b32_e32 v54, v2
	v_mov_b32_e32 v55, v2
	v_mov_b32_e32 v56, v2
	v_mov_b32_e32 v57, v2
	v_mov_b32_e32 v58, v2
	v_mov_b32_e32 v59, v2
	v_mov_b32_e32 v60, v2
	v_mov_b32_e32 v61, v2
	v_mov_b32_e32 v62, v2
	v_mov_b32_e32 v63, v2
	v_mov_b32_e32 v64, v2
	v_mov_b32_e32 v65, v2
	v_mov_b32_e32 v66, v2
	v_mov_b32_e32 v67, v2
	v_mov_b32_e32 v68, v2
	v_mov_b32_e32 v69, v2
	v_mov_b32_e32 v70, v2
	v_mov_b32_e32 v71, v2
	v_mov_b32_e32 v72, v2
	v_mov_b32_e32 v73, v2
	v_mov_b32_e32 v74, v2
	v_mov_b32_e32 v75, v2
	v_mov_b32_e32 v76, v2
	v_mov_b32_e32 v77, v2
	v_mov_b32_e32 v78, v2
	v_mov_b32_e32 v79, v2
	v_mov_b32_e32 v80, v2
	v_mov_b32_e32 v81, v2
	v_mov_b32_e32 v82, v2
	v_mov_b32_e32 v83, v2
	v_mov_b32_e32 v84, v2
	v_mov_b32_e32 v85, v2
	v_mov_b32_e32 v86, v2
	v_mov_b32_e32 v87, v2
	v_mov_b32_e32 v88, v2
	v_mov_b32_e32 v89, v2
	v_mov_b32_e32 v90, v2
	v_mov_b32_e32 v91, v2
	v_mov_b32_e32 v92, v2
	v_mov_b32_e32 v93, v2
	v_mov_b32_e32 v94, v2
	v_mov_b32_e32 v95, v2
	v_mov_b32_e32 v96, v2
	v_mov_b32_e32 v97, v2
	v_mov_b32_e32 v98, v2
	v_mov_b32_e32 v99, v2
	v_mov_b32_e32 v100, v2
	v_mov_b32_e32 v101, v2
	v_mov_b32_e32 v102, v2
	v_mov_b32_e32 v103, v2
	v_mov_b32_e32 v104, v2
	v_mov_b32_e32 v105, v2
	v_mov_b32_e32 v106, v2
	v_mov_b32_e32 v107, v2
	v_mov_b32_e32 v108, v2
	v_mov_b32_e32 v109, v2
	v_mov_b32_e32 v110, v2
	v_mov_b32_e32 v111, v2
	v_mov_b32_e32 v112, v2
	v_mov_b32_e32 v113, v2
	v_mov_b32_e32 v114, v2
	v_mov_b32_e32 v115, v2
	v_mov_b32_e32 v116, v2
	v_mov_b32_e32 v117, v2
	v_mov_b32_e32 v118, v2
	v_mov_b32_e32 v119, v2
	v_mov_b32_e32 v120, v2
	v_mov_b32_e32 v121, v2
	v_mov_b32_e32 v122, v2
	v_mov_b32_e32 v123, v2
	v_mov_b32_e32 v124, v2
	v_mov_b32_e32 v125, v2
	v_mov_b32_e32 v126, v2
	v_mov_b32_e32 v127, v2
	v_mov_b32_e32 v128, v2
	v_mov_b32_e32 v129, v2
	s_barrier

; DI float sigm(float x) { return 1.f / (1.f + __expf(-x)); }
; DI u32x4 pack8(const float* f) { u32x4 o; o.x = pack2(f[0], f[1]); o.y = pack2(f[2], f[3]); o.z = pack2(f[4], f[5]); o.w = pack2(f[6], f[7]); return o; }
; DI int tid512() { int t = threadIdx.x; asm volatile("" : "+v"(t)); return t; }
; DI u32x4* merge_scratch(PREF p, int region) { const int t = tid512(); return (u32x4*)p.fbuf + (size_t)blockIdx.x * 40960 + region * 8192 + (t >> 6) * 1024 + (t & 63); }
; DI void gate_reg(PREF p, int l, int n, f32x4 (&acc)[2][2][4][2], int dt) {
;   const u32x4* sbn = merge_scratch(p, n);
;   u32x4* ssum = merge_scratch(p, 4);
;   const int t = tid512(), wid = t >> 6, lane = t & 63, wc = wid & 3, fr = lane & 15;
;   const float* bm = p.b_merge + (size_t)l * 4096 + n * 1024 + dt * 256 + wc * 32 + fr;
;   float bias[2][2];
; #pragma unroll
;   for (int bj = 0; bj < 2; ++bj)
; #pragma unroll
;     for (int nn = 0; nn < 2; ++nn) bias[bj][nn] = bm[bj * 128 + nn * 16];
; #pragma unroll
;   for (int ai = 0; ai < 2; ++ai)
; #pragma unroll
;     for (int bj = 0; bj < 2; ++bj) {
;       __builtin_amdgcn_sched_barrier(0);
;       u32x4 bn[4], pv[4];
; #pragma unroll
;       for (int m = 0; m < 4; ++m) {
;         bn[m] = sbn[((ai * 2 + bj) * 4 + m) * 64];
;         if (n > 0) pv[m] = ssum[((ai * 2 + bj) * 4 + m) * 64];
;       }
; #pragma unroll
;       for (int m = 0; m < 4; ++m) {
;         float b[8]; unpack8(bn[m], b);
;         float v[8];
; #pragma unroll
;         for (int nn = 0; nn < 2; ++nn)
; #pragma unroll
;           for (int j = 0; j < 4; ++j) v[nn * 4 + j] = sigm(acc[ai][bj][m][nn][j] + bias[bj][nn]) * b[nn * 4 + j];
;         if (n > 0) {
;           float o[8]; unpack8(pv[m], o);
; #pragma unroll
;           for (int e = 0; e < 8; ++e) v[e] += o[e];
;         }
;         if (n < 3) ssum[((ai * 2 + bj) * 4 + m) * 64] = pack8(v);
; #pragma unroll
;         for (int nn = 0; nn < 2; ++nn)
; #pragma unroll
;           for (int j = 0; j < 4; ++j) acc[ai][bj][m][nn][j] = v[nn * 4 + j];
;       }
;     }
; }
.LBB0_108:
	s_or_b64 exec, exec, s[8:9]
	s_lshl_b32 s0, s23, 8
	s_add_u32 s98, s25, s0
	s_addc_u32 s99, s48, 0
	s_lshr_b32 s0, s23, 1
	s_lshl_b32 s0, s0, 12
	s_add_u32 s8, s63, s0
	s_addc_u32 s9, s64, 0
	s_add_u32 s10, s8, 0x20000
	s_addc_u32 s11, s9, 0
	s_add_u32 s42, s8, 0x40000
	s_addc_u32 s43, s9, 0
	s_add_u32 s44, s8, 0x60000
	s_addc_u32 s45, s9, 0
	s_lshl_b32 s0, s23, 1
	v_bfe_u32 v155, v168, 6, 2
	v_lshlrev_b32_e32 v130, 6, v155
	v_and_b32_e32 v131, 15, v168
	v_lshl_or_b32 v130, v131, 2, v130
	global_load_dword v143, v130, s[98:99]
	v_add_u32_e32 v131, 0x1000, v130
	global_load_dword v144, v131, s[98:99]
	v_add_u32_e32 v131, 0x2000, v130
	global_load_dword v145, v131, s[98:99]
	v_add_u32_e32 v131, 0x3000, v130
	global_load_dword v154, v131, s[98:99]
	v_lshrrev_b32_e32 v130, 1, v155
	v_add_u32_e32 v130, s0, v130
	v_and_b32_e32 v130, 3, v130
	v_lshrrev_b32_e32 v131, 8, v168
	v_lshl_add_u32 v130, v131, 2, v130
	v_lshlrev_b32_e32 v130, 14, v130
	v_and_b32_e32 v131, 63, v168
	v_lshl_or_b32 v142, v131, 4, v130
	v_and_b32_e32 v131, 1, v155
	v_lshl_or_b32 v142, v131, 3, v142
	v_add_u32_e32 v0, 0x2000, v142
	global_load_dwordx2 v[182:183], v142, s[8:9] offset:0
	global_load_dwordx2 v[184:185], v142, s[10:11] offset:0
	global_load_dwordx2 v[186:187], v142, s[42:43] offset:0
	global_load_dwordx2 v[188:189], v142, s[44:45] offset:0
	global_load_dwordx2 v[190:191], v142, s[8:9] offset:1024
	global_load_dwordx2 v[192:193], v142, s[10:11] offset:1024
	global_load_dwordx2 v[194:195], v142, s[42:43] offset:1024
	global_load_dwordx2 v[196:197], v142, s[44:45] offset:1024
	global_load_dwordx2 v[198:199], v142, s[8:9] offset:2048
	global_load_dwordx2 v[200:201], v142, s[10:11] offset:2048
	global_load_dwordx2 v[202:203], v142, s[42:43] offset:2048
	global_load_dwordx2 v[204:205], v142, s[44:45] offset:2048
	global_load_dwordx2 v[206:207], v142, s[8:9] offset:3072
	global_load_dwordx2 v[208:209], v142, s[10:11] offset:3072
	global_load_dwordx2 v[210:211], v142, s[42:43] offset:3072
	global_load_dwordx2 v[212:213], v142, s[44:45] offset:3072
	global_load_dwordx2 v[214:215], v0, s[8:9] offset:0
	global_load_dwordx2 v[216:217], v0, s[10:11] offset:0
	global_load_dwordx2 v[218:219], v0, s[42:43] offset:0
	global_load_dwordx2 v[220:221], v0, s[44:45] offset:0
	global_load_dwordx2 v[222:223], v0, s[8:9] offset:1024
	global_load_dwordx2 v[224:225], v0, s[10:11] offset:1024
	global_load_dwordx2 v[226:227], v0, s[42:43] offset:1024
	global_load_dwordx2 v[228:229], v0, s[44:45] offset:1024
	global_load_dwordx2 v[230:231], v0, s[8:9] offset:2048
	global_load_dwordx2 v[232:233], v0, s[10:11] offset:2048
	global_load_dwordx2 v[234:235], v0, s[42:43] offset:2048
	global_load_dwordx2 v[236:237], v0, s[44:45] offset:2048
	global_load_dwordx2 v[238:239], v0, s[8:9] offset:3072
	global_load_dwordx2 v[240:241], v0, s[10:11] offset:3072
	global_load_dwordx2 v[242:243], v0, s[42:43] offset:3072
	global_load_dwordx2 v[244:245], v0, s[44:45] offset:3072
	s_waitcnt vmcnt(28)
	v_add_f32_e32 v158, v158, v143
	v_mul_f32_e32 v158, 0xbfb8aa3b, v158
	v_exp_f32_e32 v158, v158
	v_add_f32_e32 v159, v159, v143
	v_mul_f32_e32 v159, 0xbfb8aa3b, v159
	v_exp_f32_e32 v159, v159
	v_add_f32_e32 v160, v160, v143
	v_mul_f32_e32 v160, 0xbfb8aa3b, v160
	v_exp_f32_e32 v160, v160
	v_add_f32_e32 v161, v161, v143
	v_mul_f32_e32 v161, 0xbfb8aa3b, v161
	v_exp_f32_e32 v161, v161
	v_add_f32_e32 v150, v150, v144
	v_mul_f32_e32 v150, 0xbfb8aa3b, v150
	v_exp_f32_e32 v150, v150
	v_add_f32_e32 v151, v151, v144
	v_mul_f32_e32 v151, 0xbfb8aa3b, v151
	v_exp_f32_e32 v151, v151
	v_add_f32_e32 v152, v152, v144
	v_mul_f32_e32 v152, 0xbfb8aa3b, v152
	v_exp_f32_e32 v152, v152
	v_add_f32_e32 v153, v153, v144
	v_mul_f32_e32 v153, 0xbfb8aa3b, v153
	v_exp_f32_e32 v153, v153
	v_add_f32_e32 v110, v110, v145
	v_mul_f32_e32 v110, 0xbfb8aa3b, v110
	v_exp_f32_e32 v110, v110
	v_add_f32_e32 v111, v111, v145
	v_mul_f32_e32 v111, 0xbfb8aa3b, v111
	v_exp_f32_e32 v111, v111
	v_add_f32_e32 v112, v112, v145
	v_mul_f32_e32 v112, 0xbfb8aa3b, v112
	v_exp_f32_e32 v112, v112
	v_add_f32_e32 v113, v113, v145
	v_mul_f32_e32 v113, 0xbfb8aa3b, v113
	v_exp_f32_e32 v113, v113
	v_add_f32_e32 v106, v106, v154
	v_mul_f32_e32 v106, 0xbfb8aa3b, v106
	v_exp_f32_e32 v106, v106
	v_add_f32_e32 v107, v107, v154
	v_mul_f32_e32 v107, 0xbfb8aa3b, v107
	v_exp_f32_e32 v107, v107
	v_add_f32_e32 v108, v108, v154
	v_mul_f32_e32 v108, 0xbfb8aa3b, v108
	v_exp_f32_e32 v108, v108
	v_add_f32_e32 v109, v109, v154
	v_mul_f32_e32 v109, 0xbfb8aa3b, v109
	v_exp_f32_e32 v109, v109
	v_pk_add_f32 v[158:159], v[158:159], 1.0 op_sel_hi:[1,0]
	v_lshlrev_b32_e32 v156, 16, v182
	v_and_b32_e32 v157, 0xffff0000, v182
	v_rcp_f32_e32 v158, v158
	v_rcp_f32_e32 v159, v159
	v_pk_add_f32 v[160:161], v[160:161], 1.0 op_sel_hi:[1,0]
	v_lshlrev_b32_e32 v164, 16, v183
	v_and_b32_e32 v165, 0xffff0000, v183
	v_rcp_f32_e32 v160, v160
	v_rcp_f32_e32 v161, v161
	v_pk_mul_f32 v[158:159], v[158:159], v[156:157]
	v_pk_mul_f32 v[160:161], v[160:161], v[164:165]
	v_pk_add_f32 v[150:151], v[150:151], 1.0 op_sel_hi:[1,0]
	v_lshlrev_b32_e32 v156, 16, v184
	v_and_b32_e32 v157, 0xffff0000, v184
	v_rcp_f32_e32 v150, v150
	v_rcp_f32_e32 v151, v151
	v_pk_add_f32 v[152:153], v[152:153], 1.0 op_sel_hi:[1,0]
	v_lshlrev_b32_e32 v164, 16, v185
	v_and_b32_e32 v165, 0xffff0000, v185
	v_rcp_f32_e32 v152, v152
	v_rcp_f32_e32 v153, v153
	v_pk_fma_f32 v[158:159], v[150:151], v[156:157], v[158:159]
	v_pk_fma_f32 v[160:161], v[152:153], v[164:165], v[160:161]
	v_pk_add_f32 v[110:111], v[110:111], 1.0 op_sel_hi:[1,0]
	v_lshlrev_b32_e32 v156, 16, v186
	v_and_b32_e32 v157, 0xffff0000, v186
	v_rcp_f32_e32 v110, v110
	v_rcp_f32_e32 v111, v111
	v_pk_add_f32 v[112:113], v[112:113], 1.0 op_sel_hi:[1,0]
	v_lshlrev_b32_e32 v164, 16, v187
	v_and_b32_e32 v165, 0xffff0000, v187
	v_rcp_f32_e32 v112, v112
	v_rcp_f32_e32 v113, v113
	v_pk_fma_f32 v[158:159], v[110:111], v[156:157], v[158:159]
	v_pk_fma_f32 v[160:161], v[112:113], v[164:165], v[160:161]
	v_pk_add_f32 v[106:107], v[106:107], 1.0 op_sel_hi:[1,0]
	v_lshlrev_b32_e32 v156, 16, v188
	v_and_b32_e32 v157, 0xffff0000, v188
	v_rcp_f32_e32 v106, v106
	v_rcp_f32_e32 v107, v107
	v_pk_add_f32 v[108:109], v[108:109], 1.0 op_sel_hi:[1,0]
	v_lshlrev_b32_e32 v164, 16, v189
	v_and_b32_e32 v165, 0xffff0000, v189
	v_rcp_f32_e32 v108, v108
	v_rcp_f32_e32 v109, v109
	v_pk_fma_f32 v[158:159], v[106:107], v[156:157], v[158:159]
	v_pk_fma_f32 v[160:161], v[108:109], v[164:165], v[160:161]
	s_waitcnt vmcnt(24)
; DI float sigm(float x) { return 1.f / (1.f + __expf(-x)); }
; DI u32x4 pack8(const float* f) { u32x4 o; o.x = pack2(f[0], f[1]); o.y = pack2(f[2], f[3]); o.z = pack2(f[4], f[5]); o.w = pack2(f[6], f[7]); return o; }
; DI int tid512() { int t = threadIdx.x; asm volatile("" : "+v"(t)); return t; }
; DI u32x4* merge_scratch(PREF p, int region) { const int t = tid512(); return (u32x4*)p.fbuf + (size_t)blockIdx.x * 40960 + region * 8192 + (t >> 6) * 1024 + (t & 63); }
; DI void gate_reg(PREF p, int l, int n, f32x4 (&acc)[2][2][4][2], int dt) {
;   const u32x4* sbn = merge_scratch(p, n);
;   u32x4* ssum = merge_scratch(p, 4);
;   const int t = tid512(), wid = t >> 6, lane = t & 63, wc = wid & 3, fr = lane & 15;
;   const float* bm = p.b_merge + (size_t)l * 4096 + n * 1024 + dt * 256 + wc * 32 + fr;
;   float bias[2][2];
; #pragma unroll
;   for (int bj = 0; bj < 2; ++bj)
; #pragma unroll
;     for (int nn = 0; nn < 2; ++nn) bias[bj][nn] = bm[bj * 128 + nn * 16];
; #pragma unroll
;   for (int ai = 0; ai < 2; ++ai)
; #pragma unroll
;     for (int bj = 0; bj < 2; ++bj) {
;       __builtin_amdgcn_sched_barrier(0);
;       u32x4 bn[4], pv[4];
; #pragma unroll
;       for (int m = 0; m < 4; ++m) {
;         bn[m] = sbn[((ai * 2 + bj) * 4 + m) * 64];
;         if (n > 0) pv[m] = ssum[((ai * 2 + bj) * 4 + m) * 64];
;       }
; #pragma unroll
;       for (int m = 0; m < 4; ++m) {
;         float b[8]; unpack8(bn[m], b);
;         float v[8];
; #pragma unroll
;         for (int nn = 0; nn < 2; ++nn)
; #pragma unroll
;           for (int j = 0; j < 4; ++j) v[nn * 4 + j] = sigm(acc[ai][bj][m][nn][j] + bias[bj][nn]) * b[nn * 4 + j];
;         if (n > 0) {
;           float o[8]; unpack8(pv[m], o);
; #pragma unroll
;           for (int e = 0; e < 8; ++e) v[e] += o[e];
;         }
;         if (n < 3) ssum[((ai * 2 + bj) * 4 + m) * 64] = pack8(v);
; #pragma unroll
;         for (int nn = 0; nn < 2; ++nn)
; #pragma unroll
;           for (int j = 0; j < 4; ++j) acc[ai][bj][m][nn][j] = v[nn * 4 + j];
;       }
;     }
; }
	v_add_f32_e32 v146, v146, v143
	v_mul_f32_e32 v146, 0xbfb8aa3b, v146
	v_exp_f32_e32 v146, v146
	v_add_f32_e32 v147, v147, v143
	v_mul_f32_e32 v147, 0xbfb8aa3b, v147
	v_exp_f32_e32 v147, v147
	v_add_f32_e32 v148, v148, v143
	v_mul_f32_e32 v148, 0xbfb8aa3b, v148
	v_exp_f32_e32 v148, v148
	v_add_f32_e32 v149, v149, v143
	v_mul_f32_e32 v149, 0xbfb8aa3b, v149
	v_exp_f32_e32 v149, v149
	v_add_f32_e32 v138, v138, v144
	v_mul_f32_e32 v138, 0xbfb8aa3b, v138
	v_exp_f32_e32 v138, v138
	v_add_f32_e32 v139, v139, v144
	v_mul_f32_e32 v139, 0xbfb8aa3b, v139
	v_exp_f32_e32 v139, v139
	v_add_f32_e32 v140, v140, v144
	v_mul_f32_e32 v140, 0xbfb8aa3b, v140
	v_exp_f32_e32 v140, v140
	v_add_f32_e32 v141, v141, v144
	v_mul_f32_e32 v141, 0xbfb8aa3b, v141
	v_exp_f32_e32 v141, v141
	v_add_f32_e32 v102, v102, v145
	v_mul_f32_e32 v102, 0xbfb8aa3b, v102
	v_exp_f32_e32 v102, v102
	v_add_f32_e32 v103, v103, v145
	v_mul_f32_e32 v103, 0xbfb8aa3b, v103
	v_exp_f32_e32 v103, v103
	v_add_f32_e32 v104, v104, v145
	v_mul_f32_e32 v104, 0xbfb8aa3b, v104
	v_exp_f32_e32 v104, v104
	v_add_f32_e32 v105, v105, v145
	v_mul_f32_e32 v105, 0xbfb8aa3b, v105
	v_exp_f32_e32 v105, v105
	v_add_f32_e32 v98, v98, v154
	v_mul_f32_e32 v98, 0xbfb8aa3b, v98
	v_exp_f32_e32 v98, v98
	v_add_f32_e32 v99, v99, v154
	v_mul_f32_e32 v99, 0xbfb8aa3b, v99
	v_exp_f32_e32 v99, v99
	v_add_f32_e32 v100, v100, v154
	v_mul_f32_e32 v100, 0xbfb8aa3b, v100
	v_exp_f32_e32 v100, v100
	v_add_f32_e32 v101, v101, v154
	v_mul_f32_e32 v101, 0xbfb8aa3b, v101
	v_exp_f32_e32 v101, v101
	v_pk_add_f32 v[146:147], v[146:147], 1.0 op_sel_hi:[1,0]
	v_lshlrev_b32_e32 v156, 16, v190
	v_and_b32_e32 v157, 0xffff0000, v190
	v_rcp_f32_e32 v146, v146
	v_rcp_f32_e32 v147, v147
	v_pk_add_f32 v[148:149], v[148:149], 1.0 op_sel_hi:[1,0]
	v_lshlrev_b32_e32 v164, 16, v191
	v_and_b32_e32 v165, 0xffff0000, v191
	v_rcp_f32_e32 v148, v148
	v_rcp_f32_e32 v149, v149
	v_pk_mul_f32 v[146:147], v[146:147], v[156:157]
	v_pk_mul_f32 v[148:149], v[148:149], v[164:165]
	v_pk_add_f32 v[138:139], v[138:139], 1.0 op_sel_hi:[1,0]
	v_lshlrev_b32_e32 v156, 16, v192
	v_and_b32_e32 v157, 0xffff0000, v192
	v_rcp_f32_e32 v138, v138
	v_rcp_f32_e32 v139, v139
	v_pk_add_f32 v[140:141], v[140:141], 1.0 op_sel_hi:[1,0]
	v_lshlrev_b32_e32 v164, 16, v193
	v_and_b32_e32 v165, 0xffff0000, v193
	v_rcp_f32_e32 v140, v140
	v_rcp_f32_e32 v141, v141
	v_pk_fma_f32 v[146:147], v[138:139], v[156:157], v[146:147]
	v_pk_fma_f32 v[148:149], v[140:141], v[164:165], v[148:149]
	v_pk_add_f32 v[102:103], v[102:103], 1.0 op_sel_hi:[1,0]
	v_lshlrev_b32_e32 v156, 16, v194
	v_and_b32_e32 v157, 0xffff0000, v194
	v_rcp_f32_e32 v102, v102
	v_rcp_f32_e32 v103, v103
	v_pk_add_f32 v[104:105], v[104:105], 1.0 op_sel_hi:[1,0]
	v_lshlrev_b32_e32 v164, 16, v195
	v_and_b32_e32 v165, 0xffff0000, v195
	v_rcp_f32_e32 v104, v104
	v_rcp_f32_e32 v105, v105
	v_pk_fma_f32 v[146:147], v[102:103], v[156:157], v[146:147]
	v_pk_fma_f32 v[148:149], v[104:105], v[164:165], v[148:149]
	v_pk_add_f32 v[98:99], v[98:99], 1.0 op_sel_hi:[1,0]
	v_lshlrev_b32_e32 v156, 16, v196
	v_and_b32_e32 v157, 0xffff0000, v196
	v_rcp_f32_e32 v98, v98
	v_rcp_f32_e32 v99, v99
	v_pk_add_f32 v[100:101], v[100:101], 1.0 op_sel_hi:[1,0]
	v_lshlrev_b32_e32 v164, 16, v197
	v_and_b32_e32 v165, 0xffff0000, v197
	v_rcp_f32_e32 v100, v100
	v_rcp_f32_e32 v101, v101
	v_pk_fma_f32 v[146:147], v[98:99], v[156:157], v[146:147]
	v_pk_fma_f32 v[148:149], v[100:101], v[164:165], v[148:149]
	s_waitcnt vmcnt(20)
	v_add_f32_e32 v134, v134, v143
	v_mul_f32_e32 v134, 0xbfb8aa3b, v134
	v_exp_f32_e32 v134, v134
	v_add_f32_e32 v135, v135, v143
	v_mul_f32_e32 v135, 0xbfb8aa3b, v135
	v_exp_f32_e32 v135, v135
	v_add_f32_e32 v136, v136, v143
	v_mul_f32_e32 v136, 0xbfb8aa3b, v136
	v_exp_f32_e32 v136, v136
	v_add_f32_e32 v137, v137, v143
	v_mul_f32_e32 v137, 0xbfb8aa3b, v137
	v_exp_f32_e32 v137, v137
	v_add_f32_e32 v126, v126, v144
	v_mul_f32_e32 v126, 0xbfb8aa3b, v126
	v_exp_f32_e32 v126, v126
	v_add_f32_e32 v127, v127, v144
	v_mul_f32_e32 v127, 0xbfb8aa3b, v127
	v_exp_f32_e32 v127, v127
	v_add_f32_e32 v128, v128, v144
	v_mul_f32_e32 v128, 0xbfb8aa3b, v128
	v_exp_f32_e32 v128, v128
	v_add_f32_e32 v129, v129, v144
	v_mul_f32_e32 v129, 0xbfb8aa3b, v129
	v_exp_f32_e32 v129, v129
	v_add_f32_e32 v94, v94, v145
	v_mul_f32_e32 v94, 0xbfb8aa3b, v94
	v_exp_f32_e32 v94, v94
	v_add_f32_e32 v95, v95, v145
	v_mul_f32_e32 v95, 0xbfb8aa3b, v95
	v_exp_f32_e32 v95, v95
	v_add_f32_e32 v96, v96, v145
	v_mul_f32_e32 v96, 0xbfb8aa3b, v96
	v_exp_f32_e32 v96, v96
	v_add_f32_e32 v97, v97, v145
	v_mul_f32_e32 v97, 0xbfb8aa3b, v97
	v_exp_f32_e32 v97, v97
	v_add_f32_e32 v90, v90, v154
	v_mul_f32_e32 v90, 0xbfb8aa3b, v90
	v_exp_f32_e32 v90, v90
	v_add_f32_e32 v91, v91, v154
	v_mul_f32_e32 v91, 0xbfb8aa3b, v91
	v_exp_f32_e32 v91, v91
	v_add_f32_e32 v92, v92, v154
	v_mul_f32_e32 v92, 0xbfb8aa3b, v92
	v_exp_f32_e32 v92, v92
	v_add_f32_e32 v93, v93, v154
	v_mul_f32_e32 v93, 0xbfb8aa3b, v93
	v_exp_f32_e32 v93, v93
	v_pk_add_f32 v[134:135], v[134:135], 1.0 op_sel_hi:[1,0]
	v_lshlrev_b32_e32 v156, 16, v198
	v_and_b32_e32 v157, 0xffff0000, v198
	v_rcp_f32_e32 v134, v134
	v_rcp_f32_e32 v135, v135
	v_pk_add_f32 v[136:137], v[136:137], 1.0 op_sel_hi:[1,0]
	v_lshlrev_b32_e32 v164, 16, v199
	v_and_b32_e32 v165, 0xffff0000, v199
	v_rcp_f32_e32 v136, v136
	v_rcp_f32_e32 v137, v137
	v_pk_mul_f32 v[134:135], v[134:135], v[156:157]
	v_pk_mul_f32 v[136:137], v[136:137], v[164:165]
	v_pk_add_f32 v[126:127], v[126:127], 1.0 op_sel_hi:[1,0]
	v_lshlrev_b32_e32 v156, 16, v200
	v_and_b32_e32 v157, 0xffff0000, v200
	v_rcp_f32_e32 v126, v126
	v_rcp_f32_e32 v127, v127
	v_pk_add_f32 v[128:129], v[128:129], 1.0 op_sel_hi:[1,0]
	v_lshlrev_b32_e32 v164, 16, v201
	v_and_b32_e32 v165, 0xffff0000, v201
	v_rcp_f32_e32 v128, v128
	v_rcp_f32_e32 v129, v129
	v_pk_fma_f32 v[134:135], v[126:127], v[156:157], v[134:135]
	v_pk_fma_f32 v[136:137], v[128:129], v[164:165], v[136:137]
	v_pk_add_f32 v[94:95], v[94:95], 1.0 op_sel_hi:[1,0]
	v_lshlrev_b32_e32 v156, 16, v202
	v_and_b32_e32 v157, 0xffff0000, v202
	v_rcp_f32_e32 v94, v94
	v_rcp_f32_e32 v95, v95
	v_pk_add_f32 v[96:97], v[96:97], 1.0 op_sel_hi:[1,0]
	v_lshlrev_b32_e32 v164, 16, v203
	v_and_b32_e32 v165, 0xffff0000, v203
	v_rcp_f32_e32 v96, v96
	v_rcp_f32_e32 v97, v97
	v_pk_fma_f32 v[134:135], v[94:95], v[156:157], v[134:135]
	v_pk_fma_f32 v[136:137], v[96:97], v[164:165], v[136:137]
	v_pk_add_f32 v[90:91], v[90:91], 1.0 op_sel_hi:[1,0]
	v_lshlrev_b32_e32 v156, 16, v204
	v_and_b32_e32 v157, 0xffff0000, v204
	v_rcp_f32_e32 v90, v90
	v_rcp_f32_e32 v91, v91
	v_pk_add_f32 v[92:93], v[92:93], 1.0 op_sel_hi:[1,0]
	v_lshlrev_b32_e32 v164, 16, v205
	v_and_b32_e32 v165, 0xffff0000, v205
	v_rcp_f32_e32 v92, v92
	v_rcp_f32_e32 v93, v93
	v_pk_fma_f32 v[134:135], v[90:91], v[156:157], v[134:135]
	v_pk_fma_f32 v[136:137], v[92:93], v[164:165], v[136:137]
	s_waitcnt vmcnt(16)
; DI float sigm(float x) { return 1.f / (1.f + __expf(-x)); }
; DI u32x4 pack8(const float* f) { u32x4 o; o.x = pack2(f[0], f[1]); o.y = pack2(f[2], f[3]); o.z = pack2(f[4], f[5]); o.w = pack2(f[6], f[7]); return o; }
; DI void gate_reg(PREF p, int l, int n, f32x4 (&acc)[2][2][4][2], int dt) {
;     ...
;   for (int ai = 0; ai < 2; ++ai)
; #pragma unroll
;     for (int bj = 0; bj < 2; ++bj) {
;       __builtin_amdgcn_sched_barrier(0);
;       u32x4 bn[4], pv[4];
; #pragma unroll
;       for (int m = 0; m < 4; ++m) {
;         bn[m] = sbn[((ai * 2 + bj) * 4 + m) * 64];
;         if (n > 0) pv[m] = ssum[((ai * 2 + bj) * 4 + m) * 64];
;       }
; #pragma unroll
;       for (int m = 0; m < 4; ++m) {
;         float b[8]; unpack8(bn[m], b);
;         float v[8];
; #pragma unroll
;         for (int nn = 0; nn < 2; ++nn)
; #pragma unroll
;           for (int j = 0; j < 4; ++j) v[nn * 4 + j] = sigm(acc[ai][bj][m][nn][j] + bias[bj][nn]) * b[nn * 4 + j];
;         if (n > 0) {
;           float o[8]; unpack8(pv[m], o);
; #pragma unroll
;           for (int e = 0; e < 8; ++e) v[e] += o[e];
;         }
;         if (n < 3) ssum[((ai * 2 + bj) * 4 + m) * 64] = pack8(v);
; #pragma unroll
;         for (int nn = 0; nn < 2; ++nn)
; #pragma unroll
;           for (int j = 0; j < 4; ++j) acc[ai][bj][m][nn][j] = v[nn * 4 + j];
	v_add_f32_e32 v122, v122, v143
	v_mul_f32_e32 v122, 0xbfb8aa3b, v122
	v_exp_f32_e32 v122, v122
	v_add_f32_e32 v123, v123, v143
	v_mul_f32_e32 v123, 0xbfb8aa3b, v123
	v_exp_f32_e32 v123, v123
	v_add_f32_e32 v124, v124, v143
	v_mul_f32_e32 v124, 0xbfb8aa3b, v124
	v_exp_f32_e32 v124, v124
	v_add_f32_e32 v125, v125, v143
	v_mul_f32_e32 v125, 0xbfb8aa3b, v125
	v_exp_f32_e32 v125, v125
	v_add_f32_e32 v114, v114, v144
	v_mul_f32_e32 v114, 0xbfb8aa3b, v114
	v_exp_f32_e32 v114, v114
	v_add_f32_e32 v115, v115, v144
	v_mul_f32_e32 v115, 0xbfb8aa3b, v115
	v_exp_f32_e32 v115, v115
	v_add_f32_e32 v116, v116, v144
	v_mul_f32_e32 v116, 0xbfb8aa3b, v116
	v_exp_f32_e32 v116, v116
	v_add_f32_e32 v117, v117, v144
	v_mul_f32_e32 v117, 0xbfb8aa3b, v117
	v_exp_f32_e32 v117, v117
	v_add_f32_e32 v86, v86, v145
	v_mul_f32_e32 v86, 0xbfb8aa3b, v86
	v_exp_f32_e32 v86, v86
	v_add_f32_e32 v87, v87, v145
	v_mul_f32_e32 v87, 0xbfb8aa3b, v87
	v_exp_f32_e32 v87, v87
	v_add_f32_e32 v88, v88, v145
	v_mul_f32_e32 v88, 0xbfb8aa3b, v88
	v_exp_f32_e32 v88, v88
	v_add_f32_e32 v89, v89, v145
	v_mul_f32_e32 v89, 0xbfb8aa3b, v89
	v_exp_f32_e32 v89, v89
	v_add_f32_e32 v82, v82, v154
	v_mul_f32_e32 v82, 0xbfb8aa3b, v82
	v_exp_f32_e32 v82, v82
	v_add_f32_e32 v83, v83, v154
	v_mul_f32_e32 v83, 0xbfb8aa3b, v83
	v_exp_f32_e32 v83, v83
	v_add_f32_e32 v84, v84, v154
	v_mul_f32_e32 v84, 0xbfb8aa3b, v84
	v_exp_f32_e32 v84, v84
	v_add_f32_e32 v85, v85, v154
	v_mul_f32_e32 v85, 0xbfb8aa3b, v85
	v_exp_f32_e32 v85, v85
	v_pk_add_f32 v[122:123], v[122:123], 1.0 op_sel_hi:[1,0]
	v_lshlrev_b32_e32 v156, 16, v206
	v_and_b32_e32 v157, 0xffff0000, v206
	v_rcp_f32_e32 v122, v122
	v_rcp_f32_e32 v123, v123
	v_pk_add_f32 v[124:125], v[124:125], 1.0 op_sel_hi:[1,0]
	v_lshlrev_b32_e32 v164, 16, v207
	v_and_b32_e32 v165, 0xffff0000, v207
	v_rcp_f32_e32 v124, v124
	v_rcp_f32_e32 v125, v125
	v_pk_mul_f32 v[122:123], v[122:123], v[156:157]
	v_pk_mul_f32 v[124:125], v[124:125], v[164:165]
	v_pk_add_f32 v[114:115], v[114:115], 1.0 op_sel_hi:[1,0]
	v_lshlrev_b32_e32 v156, 16, v208
	v_and_b32_e32 v157, 0xffff0000, v208
	v_rcp_f32_e32 v114, v114
	v_rcp_f32_e32 v115, v115
	v_pk_add_f32 v[116:117], v[116:117], 1.0 op_sel_hi:[1,0]
	v_lshlrev_b32_e32 v164, 16, v209
	v_and_b32_e32 v165, 0xffff0000, v209
	v_rcp_f32_e32 v116, v116
	v_rcp_f32_e32 v117, v117
	v_pk_fma_f32 v[122:123], v[114:115], v[156:157], v[122:123]
	v_pk_fma_f32 v[124:125], v[116:117], v[164:165], v[124:125]
	v_pk_add_f32 v[86:87], v[86:87], 1.0 op_sel_hi:[1,0]
	v_lshlrev_b32_e32 v156, 16, v210
	v_and_b32_e32 v157, 0xffff0000, v210
	v_rcp_f32_e32 v86, v86
	v_rcp_f32_e32 v87, v87
	v_pk_add_f32 v[88:89], v[88:89], 1.0 op_sel_hi:[1,0]
	v_lshlrev_b32_e32 v164, 16, v211
	v_and_b32_e32 v165, 0xffff0000, v211
	v_rcp_f32_e32 v88, v88
	v_rcp_f32_e32 v89, v89
	v_pk_fma_f32 v[122:123], v[86:87], v[156:157], v[122:123]
	v_pk_fma_f32 v[124:125], v[88:89], v[164:165], v[124:125]
	v_pk_add_f32 v[82:83], v[82:83], 1.0 op_sel_hi:[1,0]
	v_lshlrev_b32_e32 v156, 16, v212
	v_and_b32_e32 v157, 0xffff0000, v212
	v_rcp_f32_e32 v82, v82
	v_rcp_f32_e32 v83, v83
	v_pk_add_f32 v[84:85], v[84:85], 1.0 op_sel_hi:[1,0]
	v_lshlrev_b32_e32 v164, 16, v213
	v_and_b32_e32 v165, 0xffff0000, v213
	v_rcp_f32_e32 v84, v84
	v_rcp_f32_e32 v85, v85
	v_pk_fma_f32 v[122:123], v[82:83], v[156:157], v[122:123]
	v_pk_fma_f32 v[124:125], v[84:85], v[164:165], v[124:125]
	s_waitcnt vmcnt(12)
	v_add_f32_e32 v78, v78, v143
	v_mul_f32_e32 v78, 0xbfb8aa3b, v78
	v_exp_f32_e32 v78, v78
	v_add_f32_e32 v79, v79, v143
	v_mul_f32_e32 v79, 0xbfb8aa3b, v79
	v_exp_f32_e32 v79, v79
	v_add_f32_e32 v80, v80, v143
	v_mul_f32_e32 v80, 0xbfb8aa3b, v80
	v_exp_f32_e32 v80, v80
	v_add_f32_e32 v81, v81, v143
	v_mul_f32_e32 v81, 0xbfb8aa3b, v81
	v_exp_f32_e32 v81, v81
	v_add_f32_e32 v74, v74, v144
	v_mul_f32_e32 v74, 0xbfb8aa3b, v74
	v_exp_f32_e32 v74, v74
	v_add_f32_e32 v75, v75, v144
	v_mul_f32_e32 v75, 0xbfb8aa3b, v75
	v_exp_f32_e32 v75, v75
	v_add_f32_e32 v76, v76, v144
	v_mul_f32_e32 v76, 0xbfb8aa3b, v76
	v_exp_f32_e32 v76, v76
	v_add_f32_e32 v77, v77, v144
	v_mul_f32_e32 v77, 0xbfb8aa3b, v77
	v_exp_f32_e32 v77, v77
	v_add_f32_e32 v46, v46, v145
	v_mul_f32_e32 v46, 0xbfb8aa3b, v46
	v_exp_f32_e32 v46, v46
	v_add_f32_e32 v47, v47, v145
	v_mul_f32_e32 v47, 0xbfb8aa3b, v47
	v_exp_f32_e32 v47, v47
	v_add_f32_e32 v48, v48, v145
	v_mul_f32_e32 v48, 0xbfb8aa3b, v48
	v_exp_f32_e32 v48, v48
	v_add_f32_e32 v49, v49, v145
	v_mul_f32_e32 v49, 0xbfb8aa3b, v49
	v_exp_f32_e32 v49, v49
	v_add_f32_e32 v38, v38, v154
	v_mul_f32_e32 v38, 0xbfb8aa3b, v38
	v_exp_f32_e32 v38, v38
	v_add_f32_e32 v39, v39, v154
	v_mul_f32_e32 v39, 0xbfb8aa3b, v39
	v_exp_f32_e32 v39, v39
	v_add_f32_e32 v40, v40, v154
	v_mul_f32_e32 v40, 0xbfb8aa3b, v40
	v_exp_f32_e32 v40, v40
	v_add_f32_e32 v41, v41, v154
	v_mul_f32_e32 v41, 0xbfb8aa3b, v41
	v_exp_f32_e32 v41, v41
	v_pk_add_f32 v[78:79], v[78:79], 1.0 op_sel_hi:[1,0]
	v_lshlrev_b32_e32 v156, 16, v214
	v_and_b32_e32 v157, 0xffff0000, v214
	v_rcp_f32_e32 v78, v78
	v_rcp_f32_e32 v79, v79
	v_pk_add_f32 v[80:81], v[80:81], 1.0 op_sel_hi:[1,0]
	v_lshlrev_b32_e32 v164, 16, v215
	v_and_b32_e32 v165, 0xffff0000, v215
	v_rcp_f32_e32 v80, v80
	v_rcp_f32_e32 v81, v81
	v_pk_mul_f32 v[78:79], v[78:79], v[156:157]
	v_pk_mul_f32 v[80:81], v[80:81], v[164:165]
	v_pk_add_f32 v[74:75], v[74:75], 1.0 op_sel_hi:[1,0]
	v_lshlrev_b32_e32 v156, 16, v216
	v_and_b32_e32 v157, 0xffff0000, v216
	v_rcp_f32_e32 v74, v74
	v_rcp_f32_e32 v75, v75
	v_pk_add_f32 v[76:77], v[76:77], 1.0 op_sel_hi:[1,0]
	v_lshlrev_b32_e32 v164, 16, v217
	v_and_b32_e32 v165, 0xffff0000, v217
	v_rcp_f32_e32 v76, v76
	v_rcp_f32_e32 v77, v77
	v_pk_fma_f32 v[78:79], v[74:75], v[156:157], v[78:79]
	v_pk_fma_f32 v[80:81], v[76:77], v[164:165], v[80:81]
	v_pk_add_f32 v[46:47], v[46:47], 1.0 op_sel_hi:[1,0]
	v_lshlrev_b32_e32 v156, 16, v218
	v_and_b32_e32 v157, 0xffff0000, v218
	v_rcp_f32_e32 v46, v46
	v_rcp_f32_e32 v47, v47
	v_pk_add_f32 v[48:49], v[48:49], 1.0 op_sel_hi:[1,0]
	v_lshlrev_b32_e32 v164, 16, v219
	v_and_b32_e32 v165, 0xffff0000, v219
	v_rcp_f32_e32 v48, v48
	v_rcp_f32_e32 v49, v49
	v_pk_fma_f32 v[78:79], v[46:47], v[156:157], v[78:79]
	v_pk_fma_f32 v[80:81], v[48:49], v[164:165], v[80:81]
	v_pk_add_f32 v[38:39], v[38:39], 1.0 op_sel_hi:[1,0]
	v_lshlrev_b32_e32 v156, 16, v220
	v_and_b32_e32 v157, 0xffff0000, v220
	v_rcp_f32_e32 v38, v38
	v_rcp_f32_e32 v39, v39
	v_pk_add_f32 v[40:41], v[40:41], 1.0 op_sel_hi:[1,0]
	v_lshlrev_b32_e32 v164, 16, v221
	v_and_b32_e32 v165, 0xffff0000, v221
	v_rcp_f32_e32 v40, v40
	v_rcp_f32_e32 v41, v41
	v_pk_fma_f32 v[78:79], v[38:39], v[156:157], v[78:79]
	v_pk_fma_f32 v[80:81], v[40:41], v[164:165], v[80:81]
	s_waitcnt vmcnt(8)
; DI float sigm(float x) { return 1.f / (1.f + __expf(-x)); }
; DI u32x4 pack8(const float* f) { u32x4 o; o.x = pack2(f[0], f[1]); o.y = pack2(f[2], f[3]); o.z = pack2(f[4], f[5]); o.w = pack2(f[6], f[7]); return o; }
; DI void gate_reg(PREF p, int l, int n, f32x4 (&acc)[2][2][4][2], int dt) {
;     ...
;   for (int ai = 0; ai < 2; ++ai)
; #pragma unroll
;     for (int bj = 0; bj < 2; ++bj) {
;       __builtin_amdgcn_sched_barrier(0);
;       u32x4 bn[4], pv[4];
; #pragma unroll
;       for (int m = 0; m < 4; ++m) {
;         bn[m] = sbn[((ai * 2 + bj) * 4 + m) * 64];
;         if (n > 0) pv[m] = ssum[((ai * 2 + bj) * 4 + m) * 64];
;       }
; #pragma unroll
;       for (int m = 0; m < 4; ++m) {
;         float b[8]; unpack8(bn[m], b);
;         float v[8];
; #pragma unroll
;         for (int nn = 0; nn < 2; ++nn)
; #pragma unroll
;           for (int j = 0; j < 4; ++j) v[nn * 4 + j] = sigm(acc[ai][bj][m][nn][j] + bias[bj][nn]) * b[nn * 4 + j];
;         if (n > 0) {
;           float o[8]; unpack8(pv[m], o);
; #pragma unroll
;           for (int e = 0; e < 8; ++e) v[e] += o[e];
;         }
;         if (n < 3) ssum[((ai * 2 + bj) * 4 + m) * 64] = pack8(v);
; #pragma unroll
;         for (int nn = 0; nn < 2; ++nn)
; #pragma unroll
;           for (int j = 0; j < 4; ++j) acc[ai][bj][m][nn][j] = v[nn * 4 + j];
	v_add_f32_e32 v70, v70, v143
	v_mul_f32_e32 v70, 0xbfb8aa3b, v70
	v_exp_f32_e32 v70, v70
	v_add_f32_e32 v71, v71, v143
	v_mul_f32_e32 v71, 0xbfb8aa3b, v71
	v_exp_f32_e32 v71, v71
	v_add_f32_e32 v72, v72, v143
	v_mul_f32_e32 v72, 0xbfb8aa3b, v72
	v_exp_f32_e32 v72, v72
	v_add_f32_e32 v73, v73, v143
	v_mul_f32_e32 v73, 0xbfb8aa3b, v73
	v_exp_f32_e32 v73, v73
	v_add_f32_e32 v66, v66, v144
	v_mul_f32_e32 v66, 0xbfb8aa3b, v66
	v_exp_f32_e32 v66, v66
	v_add_f32_e32 v67, v67, v144
	v_mul_f32_e32 v67, 0xbfb8aa3b, v67
	v_exp_f32_e32 v67, v67
	v_add_f32_e32 v68, v68, v144
	v_mul_f32_e32 v68, 0xbfb8aa3b, v68
	v_exp_f32_e32 v68, v68
	v_add_f32_e32 v69, v69, v144
	v_mul_f32_e32 v69, 0xbfb8aa3b, v69
	v_exp_f32_e32 v69, v69
	v_add_f32_e32 v34, v34, v145
	v_mul_f32_e32 v34, 0xbfb8aa3b, v34
	v_exp_f32_e32 v34, v34
	v_add_f32_e32 v35, v35, v145
	v_mul_f32_e32 v35, 0xbfb8aa3b, v35
	v_exp_f32_e32 v35, v35
	v_add_f32_e32 v36, v36, v145
	v_mul_f32_e32 v36, 0xbfb8aa3b, v36
	v_exp_f32_e32 v36, v36
	v_add_f32_e32 v37, v37, v145
	v_mul_f32_e32 v37, 0xbfb8aa3b, v37
	v_exp_f32_e32 v37, v37
	v_add_f32_e32 v26, v26, v154
	v_mul_f32_e32 v26, 0xbfb8aa3b, v26
	v_exp_f32_e32 v26, v26
	v_add_f32_e32 v27, v27, v154
	v_mul_f32_e32 v27, 0xbfb8aa3b, v27
	v_exp_f32_e32 v27, v27
	v_add_f32_e32 v28, v28, v154
	v_mul_f32_e32 v28, 0xbfb8aa3b, v28
	v_exp_f32_e32 v28, v28
	v_add_f32_e32 v29, v29, v154
	v_mul_f32_e32 v29, 0xbfb8aa3b, v29
	v_exp_f32_e32 v29, v29
	v_pk_add_f32 v[70:71], v[70:71], 1.0 op_sel_hi:[1,0]
	v_lshlrev_b32_e32 v156, 16, v222
	v_and_b32_e32 v157, 0xffff0000, v222
	v_rcp_f32_e32 v70, v70
	v_rcp_f32_e32 v71, v71
	v_pk_add_f32 v[72:73], v[72:73], 1.0 op_sel_hi:[1,0]
	v_lshlrev_b32_e32 v164, 16, v223
	v_and_b32_e32 v165, 0xffff0000, v223
	v_rcp_f32_e32 v72, v72
	v_rcp_f32_e32 v73, v73
	v_pk_mul_f32 v[70:71], v[70:71], v[156:157]
	v_pk_mul_f32 v[72:73], v[72:73], v[164:165]
	v_pk_add_f32 v[66:67], v[66:67], 1.0 op_sel_hi:[1,0]
	v_lshlrev_b32_e32 v156, 16, v224
	v_and_b32_e32 v157, 0xffff0000, v224
	v_rcp_f32_e32 v66, v66
	v_rcp_f32_e32 v67, v67
	v_pk_add_f32 v[68:69], v[68:69], 1.0 op_sel_hi:[1,0]
	v_lshlrev_b32_e32 v164, 16, v225
	v_and_b32_e32 v165, 0xffff0000, v225
	v_rcp_f32_e32 v68, v68
	v_rcp_f32_e32 v69, v69
	v_pk_fma_f32 v[70:71], v[66:67], v[156:157], v[70:71]
	v_pk_fma_f32 v[72:73], v[68:69], v[164:165], v[72:73]
	v_pk_add_f32 v[34:35], v[34:35], 1.0 op_sel_hi:[1,0]
	v_lshlrev_b32_e32 v156, 16, v226
	v_and_b32_e32 v157, 0xffff0000, v226
	v_rcp_f32_e32 v34, v34
	v_rcp_f32_e32 v35, v35
	v_pk_add_f32 v[36:37], v[36:37], 1.0 op_sel_hi:[1,0]
	v_lshlrev_b32_e32 v164, 16, v227
	v_and_b32_e32 v165, 0xffff0000, v227
	v_rcp_f32_e32 v36, v36
	v_rcp_f32_e32 v37, v37
	v_pk_fma_f32 v[70:71], v[34:35], v[156:157], v[70:71]
	v_pk_fma_f32 v[72:73], v[36:37], v[164:165], v[72:73]
	v_pk_add_f32 v[26:27], v[26:27], 1.0 op_sel_hi:[1,0]
	v_lshlrev_b32_e32 v156, 16, v228
	v_and_b32_e32 v157, 0xffff0000, v228
	v_rcp_f32_e32 v26, v26
	v_rcp_f32_e32 v27, v27
	v_pk_add_f32 v[28:29], v[28:29], 1.0 op_sel_hi:[1,0]
	v_lshlrev_b32_e32 v164, 16, v229
	v_and_b32_e32 v165, 0xffff0000, v229
	v_rcp_f32_e32 v28, v28
	v_rcp_f32_e32 v29, v29
	v_pk_fma_f32 v[70:71], v[26:27], v[156:157], v[70:71]
	v_pk_fma_f32 v[72:73], v[28:29], v[164:165], v[72:73]
	s_waitcnt vmcnt(4)
	v_add_f32_e32 v62, v62, v143
	v_mul_f32_e32 v62, 0xbfb8aa3b, v62
	v_exp_f32_e32 v62, v62
	v_add_f32_e32 v63, v63, v143
	v_mul_f32_e32 v63, 0xbfb8aa3b, v63
	v_exp_f32_e32 v63, v63
	v_add_f32_e32 v64, v64, v143
	v_mul_f32_e32 v64, 0xbfb8aa3b, v64
	v_exp_f32_e32 v64, v64
	v_add_f32_e32 v65, v65, v143
	v_mul_f32_e32 v65, 0xbfb8aa3b, v65
	v_exp_f32_e32 v65, v65
	v_add_f32_e32 v58, v58, v144
	v_mul_f32_e32 v58, 0xbfb8aa3b, v58
	v_exp_f32_e32 v58, v58
	v_add_f32_e32 v59, v59, v144
	v_mul_f32_e32 v59, 0xbfb8aa3b, v59
	v_exp_f32_e32 v59, v59
	v_add_f32_e32 v60, v60, v144
	v_mul_f32_e32 v60, 0xbfb8aa3b, v60
	v_exp_f32_e32 v60, v60
	v_add_f32_e32 v61, v61, v144
	v_mul_f32_e32 v61, 0xbfb8aa3b, v61
	v_exp_f32_e32 v61, v61
	v_add_f32_e32 v22, v22, v145
	v_mul_f32_e32 v22, 0xbfb8aa3b, v22
	v_exp_f32_e32 v22, v22
	v_add_f32_e32 v23, v23, v145
	v_mul_f32_e32 v23, 0xbfb8aa3b, v23
	v_exp_f32_e32 v23, v23
	v_add_f32_e32 v24, v24, v145
	v_mul_f32_e32 v24, 0xbfb8aa3b, v24
	v_exp_f32_e32 v24, v24
	v_add_f32_e32 v25, v25, v145
	v_mul_f32_e32 v25, 0xbfb8aa3b, v25
	v_exp_f32_e32 v25, v25
	v_add_f32_e32 v14, v14, v154
	v_mul_f32_e32 v14, 0xbfb8aa3b, v14
	v_exp_f32_e32 v14, v14
	v_add_f32_e32 v15, v15, v154
	v_mul_f32_e32 v15, 0xbfb8aa3b, v15
	v_exp_f32_e32 v15, v15
	v_add_f32_e32 v16, v16, v154
	v_mul_f32_e32 v16, 0xbfb8aa3b, v16
	v_exp_f32_e32 v16, v16
	v_add_f32_e32 v17, v17, v154
	v_mul_f32_e32 v17, 0xbfb8aa3b, v17
	v_exp_f32_e32 v17, v17
	v_pk_add_f32 v[62:63], v[62:63], 1.0 op_sel_hi:[1,0]
	v_lshlrev_b32_e32 v156, 16, v230
	v_and_b32_e32 v157, 0xffff0000, v230
	v_rcp_f32_e32 v62, v62
	v_rcp_f32_e32 v63, v63
	v_pk_add_f32 v[64:65], v[64:65], 1.0 op_sel_hi:[1,0]
	v_lshlrev_b32_e32 v164, 16, v231
	v_and_b32_e32 v165, 0xffff0000, v231
	v_rcp_f32_e32 v64, v64
	v_rcp_f32_e32 v65, v65
	v_pk_mul_f32 v[62:63], v[62:63], v[156:157]
	v_pk_mul_f32 v[64:65], v[64:65], v[164:165]
	v_pk_add_f32 v[58:59], v[58:59], 1.0 op_sel_hi:[1,0]
	v_lshlrev_b32_e32 v156, 16, v232
	v_and_b32_e32 v157, 0xffff0000, v232
	v_rcp_f32_e32 v58, v58
	v_rcp_f32_e32 v59, v59
	v_pk_add_f32 v[60:61], v[60:61], 1.0 op_sel_hi:[1,0]
	v_lshlrev_b32_e32 v164, 16, v233
	v_and_b32_e32 v165, 0xffff0000, v233
	v_rcp_f32_e32 v60, v60
	v_rcp_f32_e32 v61, v61
	v_pk_fma_f32 v[62:63], v[58:59], v[156:157], v[62:63]
	v_pk_fma_f32 v[64:65], v[60:61], v[164:165], v[64:65]
	v_pk_add_f32 v[22:23], v[22:23], 1.0 op_sel_hi:[1,0]
	v_lshlrev_b32_e32 v156, 16, v234
	v_and_b32_e32 v157, 0xffff0000, v234
	v_rcp_f32_e32 v22, v22
	v_rcp_f32_e32 v23, v23
	v_pk_add_f32 v[24:25], v[24:25], 1.0 op_sel_hi:[1,0]
	v_lshlrev_b32_e32 v164, 16, v235
	v_and_b32_e32 v165, 0xffff0000, v235
	v_rcp_f32_e32 v24, v24
	v_rcp_f32_e32 v25, v25
	v_pk_fma_f32 v[62:63], v[22:23], v[156:157], v[62:63]
	v_pk_fma_f32 v[64:65], v[24:25], v[164:165], v[64:65]
	v_pk_add_f32 v[14:15], v[14:15], 1.0 op_sel_hi:[1,0]
	v_lshlrev_b32_e32 v156, 16, v236
	v_and_b32_e32 v157, 0xffff0000, v236
	v_rcp_f32_e32 v14, v14
	v_rcp_f32_e32 v15, v15
	v_pk_add_f32 v[16:17], v[16:17], 1.0 op_sel_hi:[1,0]
	v_lshlrev_b32_e32 v164, 16, v237
	v_and_b32_e32 v165, 0xffff0000, v237
	v_rcp_f32_e32 v16, v16
	v_rcp_f32_e32 v17, v17
	v_pk_fma_f32 v[62:63], v[14:15], v[156:157], v[62:63]
	v_pk_fma_f32 v[64:65], v[16:17], v[164:165], v[64:65]
	s_waitcnt vmcnt(0)
; DI float sigm(float x) { return 1.f / (1.f + __expf(-x)); }
; DI u32x4 pack8(const float* f) { u32x4 o; o.x = pack2(f[0], f[1]); o.y = pack2(f[2], f[3]); o.z = pack2(f[4], f[5]); o.w = pack2(f[6], f[7]); return o; }
; DI int tid512() { int t = threadIdx.x; asm volatile("" : "+v"(t)); return t; }
; DI void gate_reg(PREF p, int l, int n, f32x4 (&acc)[2][2][4][2], int dt) {
;     ...
;       for (int m = 0; m < 4; ++m) {
;         float b[8]; unpack8(bn[m], b);
;         float v[8];
; #pragma unroll
;         for (int nn = 0; nn < 2; ++nn)
; #pragma unroll
;           for (int j = 0; j < 4; ++j) v[nn * 4 + j] = sigm(acc[ai][bj][m][nn][j] + bias[bj][nn]) * b[nn * 4 + j];
;         if (n > 0) {
;           float o[8]; unpack8(pv[m], o);
; #pragma unroll
;           for (int e = 0; e < 8; ++e) v[e] += o[e];
;         }
;         if (n < 3) ssum[((ai * 2 + bj) * 4 + m) * 64] = pack8(v);
; #pragma unroll
;         for (int nn = 0; nn < 2; ++nn)
; #pragma unroll
;           for (int j = 0; j < 4; ++j) acc[ai][bj][m][nn][j] = v[nn * 4 + j];
; template <int AI, int BJ>
; DI void mg_quadrant(PREF p, const f32x4 (&acc)[2][2][4][2], int mt, int dt, float* Cs) {
;   const int t = tid512();
;   const int row0 = mt * 256 + AI * 128, col0 = dt * 256 + BJ * 128;
;   stage_q<AI, BJ>(acc, Cs);
; #pragma unroll
;   for (int q = 0; q < 4; ++q) {
;     int r = (t >> 4) + 32 * q, c = (t & 15) * 8;
;     float v[8]; ld8(Cs + r * CST + c, v);
;     *(u32x4*)(p.mg + (size_t)(row0 + r) * 1024 + col0 + c) = pack8(v);
;   }
	v_add_f32_e32 v54, v54, v143
	v_mul_f32_e32 v54, 0xbfb8aa3b, v54
	v_exp_f32_e32 v54, v54
	v_add_f32_e32 v55, v55, v143
	v_mul_f32_e32 v55, 0xbfb8aa3b, v55
	v_exp_f32_e32 v55, v55
	v_add_f32_e32 v56, v56, v143
	v_mul_f32_e32 v56, 0xbfb8aa3b, v56
	v_exp_f32_e32 v56, v56
	v_add_f32_e32 v57, v57, v143
	v_mul_f32_e32 v57, 0xbfb8aa3b, v57
	v_exp_f32_e32 v57, v57
	v_add_f32_e32 v50, v50, v144
	v_mul_f32_e32 v50, 0xbfb8aa3b, v50
	v_exp_f32_e32 v50, v50
	v_add_f32_e32 v51, v51, v144
	v_mul_f32_e32 v51, 0xbfb8aa3b, v51
	v_exp_f32_e32 v51, v51
	v_add_f32_e32 v52, v52, v144
	v_mul_f32_e32 v52, 0xbfb8aa3b, v52
	v_exp_f32_e32 v52, v52
	v_add_f32_e32 v53, v53, v144
	v_mul_f32_e32 v53, 0xbfb8aa3b, v53
	v_exp_f32_e32 v53, v53
	v_add_f32_e32 v10, v10, v145
	v_mul_f32_e32 v10, 0xbfb8aa3b, v10
	v_exp_f32_e32 v10, v10
	v_add_f32_e32 v11, v11, v145
	v_mul_f32_e32 v11, 0xbfb8aa3b, v11
	v_exp_f32_e32 v11, v11
	v_add_f32_e32 v12, v12, v145
	v_mul_f32_e32 v12, 0xbfb8aa3b, v12
	v_exp_f32_e32 v12, v12
	v_add_f32_e32 v13, v13, v145
	v_mul_f32_e32 v13, 0xbfb8aa3b, v13
	v_exp_f32_e32 v13, v13
	v_add_f32_e32 v2, v2, v154
	v_mul_f32_e32 v2, 0xbfb8aa3b, v2
	v_exp_f32_e32 v2, v2
	v_add_f32_e32 v3, v3, v154
	v_mul_f32_e32 v3, 0xbfb8aa3b, v3
	v_exp_f32_e32 v3, v3
	v_add_f32_e32 v4, v4, v154
	v_mul_f32_e32 v4, 0xbfb8aa3b, v4
	v_exp_f32_e32 v4, v4
	v_add_f32_e32 v5, v5, v154
	v_mul_f32_e32 v5, 0xbfb8aa3b, v5
	v_exp_f32_e32 v5, v5
	v_pk_add_f32 v[54:55], v[54:55], 1.0 op_sel_hi:[1,0]
	v_lshlrev_b32_e32 v156, 16, v238
	v_and_b32_e32 v157, 0xffff0000, v238
	v_rcp_f32_e32 v54, v54
	v_rcp_f32_e32 v55, v55
	v_pk_add_f32 v[56:57], v[56:57], 1.0 op_sel_hi:[1,0]
	v_lshlrev_b32_e32 v164, 16, v239
	v_and_b32_e32 v165, 0xffff0000, v239
	v_rcp_f32_e32 v56, v56
	v_rcp_f32_e32 v57, v57
	v_pk_mul_f32 v[54:55], v[54:55], v[156:157]
	v_pk_mul_f32 v[56:57], v[56:57], v[164:165]
	v_pk_add_f32 v[50:51], v[50:51], 1.0 op_sel_hi:[1,0]
	v_lshlrev_b32_e32 v156, 16, v240
	v_and_b32_e32 v157, 0xffff0000, v240
	v_rcp_f32_e32 v50, v50
	v_rcp_f32_e32 v51, v51
	v_pk_add_f32 v[52:53], v[52:53], 1.0 op_sel_hi:[1,0]
	v_lshlrev_b32_e32 v164, 16, v241
	v_and_b32_e32 v165, 0xffff0000, v241
	v_rcp_f32_e32 v52, v52
	v_rcp_f32_e32 v53, v53
	v_pk_fma_f32 v[54:55], v[50:51], v[156:157], v[54:55]
	v_pk_fma_f32 v[56:57], v[52:53], v[164:165], v[56:57]
	v_pk_add_f32 v[10:11], v[10:11], 1.0 op_sel_hi:[1,0]
	v_lshlrev_b32_e32 v156, 16, v242
	v_and_b32_e32 v157, 0xffff0000, v242
	v_rcp_f32_e32 v10, v10
	v_rcp_f32_e32 v11, v11
	v_pk_add_f32 v[12:13], v[12:13], 1.0 op_sel_hi:[1,0]
	v_lshlrev_b32_e32 v164, 16, v243
	v_and_b32_e32 v165, 0xffff0000, v243
	v_rcp_f32_e32 v12, v12
	v_rcp_f32_e32 v13, v13
	v_pk_fma_f32 v[54:55], v[10:11], v[156:157], v[54:55]
	v_pk_fma_f32 v[56:57], v[12:13], v[164:165], v[56:57]
	v_pk_add_f32 v[2:3], v[2:3], 1.0 op_sel_hi:[1,0]
	v_lshlrev_b32_e32 v156, 16, v244
	v_and_b32_e32 v157, 0xffff0000, v244
	v_rcp_f32_e32 v2, v2
	v_rcp_f32_e32 v3, v3
	v_pk_add_f32 v[4:5], v[4:5], 1.0 op_sel_hi:[1,0]
	v_lshlrev_b32_e32 v164, 16, v245
	v_and_b32_e32 v165, 0xffff0000, v245
	v_rcp_f32_e32 v4, v4
	v_rcp_f32_e32 v5, v5
	v_pk_fma_f32 v[54:55], v[2:3], v[156:157], v[54:55]
	v_pk_fma_f32 v[56:57], v[4:5], v[164:165], v[56:57]
	v_lshrrev_b32_e32 v156, 8, v168
	v_lshlrev_b32_e32 v156, 6, v156
	v_bfe_u32 v157, v168, 4, 2
	v_lshl_add_u32 v156, v157, 2, v156
	v_mul_u32_u24_e32 v156, 0x84, v156
	v_lshlrev_b32_e32 v157, 4, v155
	v_and_b32_e32 v164, 15, v168
	v_add3_u32 v156, v156, v157, v164
	v_lshlrev_b32_e32 v156, 2, v156
	v_lshrrev_b32_e32 v157, 3, v168
	v_lshlrev_b32_e32 v165, 11, v157
	v_mul_u32_u24_e32 v157, 0x84, v157
	v_and_b32_e32 v164, 7, v168
	v_lshl_add_u32 v157, v164, 3, v157
	v_lshlrev_b32_e32 v157, 2, v157
	v_lshl_add_u32 v165, v164, 4, v165
	v_mov_b32_e32 v164, v165
	s_waitcnt lgkmcnt(0)
	s_barrier
	ds_write_b32 v156, v158 offset:0
	ds_write_b32 v156, v159 offset:528
	ds_write_b32 v156, v160 offset:1056
	ds_write_b32 v156, v161 offset:1584
	ds_write_b32 v156, v146 offset:8448
	ds_write_b32 v156, v147 offset:8976
	ds_write_b32 v156, v148 offset:9504
	ds_write_b32 v156, v149 offset:10032
	ds_write_b32 v156, v134 offset:16896
	ds_write_b32 v156, v135 offset:17424
	ds_write_b32 v156, v136 offset:17952
	ds_write_b32 v156, v137 offset:18480
	ds_write_b32 v156, v122 offset:25344
	ds_write_b32 v156, v123 offset:25872
	ds_write_b32 v156, v124 offset:26400
	ds_write_b32 v156, v125 offset:26928
	s_waitcnt lgkmcnt(0)
	s_barrier
	s_add_i32 s0, s12, 0
	s_lshl_b32 s0, s0, 11
	s_lshl_b32 s1, s23, 7
	s_add_u32 s0, s0, s1
	s_add_u32 s0, s36, s0
	s_addc_u32 s1, s37, 0
	ds_read_b128 v[182:185], v157 offset:0
	ds_read_b128 v[186:189], v157 offset:16
	ds_read_b128 v[190:193], v157 offset:33792
	ds_read_b128 v[194:197], v157 offset:33808
	s_waitcnt lgkmcnt(2)
	v_cvt_pk_bf16_f32 v182, v182, v183
	v_cvt_pk_bf16_f32 v183, v184, v185
	v_cvt_pk_bf16_f32 v184, v186, v187
	v_cvt_pk_bf16_f32 v185, v188, v189
	global_store_dwordx4 v164, v[182:185], s[0:1]
	s_waitcnt lgkmcnt(0)
	v_cvt_pk_bf16_f32 v190, v190, v191
	v_cvt_pk_bf16_f32 v191, v192, v193
	v_cvt_pk_bf16_f32 v192, v194, v195
	v_cvt_pk_bf16_f32 v193, v196, v197
	v_add_u32_e32 v164, 0x20000, v164
	global_store_dwordx4 v164, v[190:193], s[0:1]
	v_mov_b32_e32 v164, v165
	s_waitcnt lgkmcnt(0)
	s_barrier
	ds_write_b32 v156, v78 offset:0
	ds_write_b32 v156, v79 offset:528
	ds_write_b32 v156, v80 offset:1056
	ds_write_b32 v156, v81 offset:1584
	ds_write_b32 v156, v70 offset:8448
	ds_write_b32 v156, v71 offset:8976
	ds_write_b32 v156, v72 offset:9504
	ds_write_b32 v156, v73 offset:10032
	ds_write_b32 v156, v62 offset:16896
	ds_write_b32 v156, v63 offset:17424
	ds_write_b32 v156, v64 offset:17952
	ds_write_b32 v156, v65 offset:18480
	ds_write_b32 v156, v54 offset:25344
	ds_write_b32 v156, v55 offset:25872
	ds_write_b32 v156, v56 offset:26400
	ds_write_b32 v156, v57 offset:26928
	s_waitcnt lgkmcnt(0)
	s_barrier
	s_add_i32 s0, s12, 128
	s_lshl_b32 s0, s0, 11
	s_lshl_b32 s1, s23, 7
	s_add_u32 s0, s0, s1
	s_add_u32 s0, s36, s0
	s_addc_u32 s1, s37, 0
	ds_read_b128 v[182:185], v157 offset:0
	ds_read_b128 v[186:189], v157 offset:16
	ds_read_b128 v[190:193], v157 offset:33792
	ds_read_b128 v[194:197], v157 offset:33808
	s_waitcnt lgkmcnt(2)
	v_cvt_pk_bf16_f32 v182, v182, v183
	v_cvt_pk_bf16_f32 v183, v184, v185
	v_cvt_pk_bf16_f32 v184, v186, v187
	v_cvt_pk_bf16_f32 v185, v188, v189
	global_store_dwordx4 v164, v[182:185], s[0:1]
	s_waitcnt lgkmcnt(0)
	v_cvt_pk_bf16_f32 v190, v190, v191
	v_cvt_pk_bf16_f32 v191, v192, v193
	v_cvt_pk_bf16_f32 v192, v194, v195
	v_cvt_pk_bf16_f32 v193, v196, v197
	v_add_u32_e32 v164, 0x20000, v164
	global_store_dwordx4 v164, v[190:193], s[0:1]
	s_branch .LBB0_101
